# MLA rescale path with packed f32 ops (score shift as v_pk_add with negated broadcast operand, QK-bias block copied by v_mov_b64): 23 fewer VALU issues per rescale event, same values
# speedup vs baseline: 1.0158x; 1.0001x over previous
; __device__ __forceinline__ void qkt9(f32x16& p0, f32x16& p1, const char* Kn, const char* Kr, const v8i32* qf, const float init, int r32, int hi) {
;     ...
;   for (int r = 0; r < 16; ++r) { p0[r] = init; p1[r] = init; }
; __device__ __forceinline__ void partialSM9(f32x16& p0, f32x16& p1, float& m_run, float& alpha, const float thr2) {
;     ...
;   if (__builtin_expect(__all(pmax <= 7.0f + thr2), 1)) { alpha = 1.f; }
;   else { const float delta = fmaxf(pmax - 7.0f, 0.f); alpha = __builtin_amdgcn_exp2f(-delta); m_run += delta;
; #pragma unroll
;     for (int r = 0; r < 16; ++r) { p0[r] -= delta; p1[r] -= delta; } }
.Lmla_h0_newmax:
	v_add_f32_e32 v0, 0xc0a00000, v177
	v_max_f32_e32 v177, 0, v0
	v_exp_f32_e64 v221, -v177
	v_add_f32_e32 v217, v217, v177
	v_pk_add_f32 v[128:129], v[128:129], v[176:177] op_sel:[0,1] op_sel_hi:[1,1] neg_lo:[0,1] neg_hi:[0,1]
	v_pk_add_f32 v[126:127], v[126:127], v[176:177] op_sel:[0,1] op_sel_hi:[1,1] neg_lo:[0,1] neg_hi:[0,1]
	v_pk_add_f32 v[124:125], v[124:125], v[176:177] op_sel:[0,1] op_sel_hi:[1,1] neg_lo:[0,1] neg_hi:[0,1]
	v_pk_add_f32 v[122:123], v[122:123], v[176:177] op_sel:[0,1] op_sel_hi:[1,1] neg_lo:[0,1] neg_hi:[0,1]
	v_pk_add_f32 v[120:121], v[120:121], v[176:177] op_sel:[0,1] op_sel_hi:[1,1] neg_lo:[0,1] neg_hi:[0,1]
	v_pk_add_f32 v[118:119], v[118:119], v[176:177] op_sel:[0,1] op_sel_hi:[1,1] neg_lo:[0,1] neg_hi:[0,1]
	v_pk_add_f32 v[116:117], v[116:117], v[176:177] op_sel:[0,1] op_sel_hi:[1,1] neg_lo:[0,1] neg_hi:[0,1]
	v_pk_add_f32 v[114:115], v[114:115], v[176:177] op_sel:[0,1] op_sel_hi:[1,1] neg_lo:[0,1] neg_hi:[0,1]
	s_and_saveexec_b64 s[20:21], s[40:41]
	ds_write_b32 v208, v221 offset:41088
	s_or_b64 exec, exec, s[20:21]
	v_pk_add_f32 v[112:113], v[112:113], v[176:177] op_sel:[0,1] op_sel_hi:[1,1] neg_lo:[0,1] neg_hi:[0,1]
	v_pk_add_f32 v[110:111], v[110:111], v[176:177] op_sel:[0,1] op_sel_hi:[1,1] neg_lo:[0,1] neg_hi:[0,1]
	v_pk_add_f32 v[108:109], v[108:109], v[176:177] op_sel:[0,1] op_sel_hi:[1,1] neg_lo:[0,1] neg_hi:[0,1]
	v_pk_add_f32 v[106:107], v[106:107], v[176:177] op_sel:[0,1] op_sel_hi:[1,1] neg_lo:[0,1] neg_hi:[0,1]
	v_pk_add_f32 v[104:105], v[104:105], v[176:177] op_sel:[0,1] op_sel_hi:[1,1] neg_lo:[0,1] neg_hi:[0,1]
	v_pk_add_f32 v[102:103], v[102:103], v[176:177] op_sel:[0,1] op_sel_hi:[1,1] neg_lo:[0,1] neg_hi:[0,1]
	v_pk_add_f32 v[100:101], v[100:101], v[176:177] op_sel:[0,1] op_sel_hi:[1,1] neg_lo:[0,1] neg_hi:[0,1]
	v_pk_add_f32 v[98:99], v[98:99], v[176:177] op_sel:[0,1] op_sel_hi:[1,1] neg_lo:[0,1] neg_hi:[0,1]
	v_sub_f32_e32 v230, 0x40e00000, v217
	v_mov_b32_e32 v231, v230
	v_mov_b64_e32 v[232:233], v[230:231]
	v_mov_b64_e32 v[234:235], v[230:231]
	v_mov_b64_e32 v[236:237], v[230:231]
	v_mov_b64_e32 v[238:239], v[230:231]
	v_mov_b64_e32 v[240:241], v[230:231]
	v_mov_b64_e32 v[242:243], v[230:231]
	v_mov_b64_e32 v[244:245], v[230:231]
	v_add_u32_e32 v0, v187, v207
	s_waitcnt lgkmcnt(0)
	ds_read_b128 v[66:69], v0 offset:41184
	ds_read_b128 v[70:73], v0 offset:41152
	ds_read_b128 v[74:77], v0 offset:41120
	ds_read_b128 v[78:81], v0 offset:41088
	s_waitcnt lgkmcnt(0)
	v_pk_mul_f32 v[62:63], v[62:63], v[66:67]
	v_pk_mul_f32 v[58:59], v[58:59], v[70:71]
	v_pk_mul_f32 v[54:55], v[54:55], v[74:75]
	v_pk_mul_f32 v[64:65], v[64:65], v[68:69]
	v_pk_mul_f32 v[60:61], v[60:61], v[72:73]
	v_pk_mul_f32 v[56:57], v[56:57], v[76:77]
	v_pk_mul_f32 v[52:53], v[52:53], v[80:81]
	v_pk_mul_f32 v[50:51], v[50:51], v[78:79]
	v_pk_mul_f32 v[46:47], v[46:47], v[66:67]
	v_pk_mul_f32 v[42:43], v[42:43], v[70:71]
	v_pk_mul_f32 v[38:39], v[38:39], v[74:75]
	v_pk_mul_f32 v[48:49], v[48:49], v[68:69]
	v_pk_mul_f32 v[44:45], v[44:45], v[72:73]
	v_pk_mul_f32 v[40:41], v[40:41], v[76:77]
	v_pk_mul_f32 v[36:37], v[36:37], v[80:81]
	v_pk_mul_f32 v[34:35], v[34:35], v[78:79]
	v_pk_mul_f32 v[30:31], v[30:31], v[66:67]
	v_pk_mul_f32 v[26:27], v[26:27], v[70:71]
	v_pk_mul_f32 v[22:23], v[22:23], v[74:75]
	v_pk_mul_f32 v[32:33], v[32:33], v[68:69]
	v_pk_mul_f32 v[28:29], v[28:29], v[72:73]
	v_pk_mul_f32 v[24:25], v[24:25], v[76:77]
	v_pk_mul_f32 v[20:21], v[20:21], v[80:81]
	v_pk_mul_f32 v[18:19], v[18:19], v[78:79]
	v_pk_mul_f32 v[14:15], v[14:15], v[66:67]
	v_pk_mul_f32 v[10:11], v[10:11], v[70:71]
	v_pk_mul_f32 v[6:7], v[6:7], v[74:75]
	v_pk_mul_f32 v[16:17], v[16:17], v[68:69]
	v_pk_mul_f32 v[12:13], v[12:13], v[72:73]
	v_pk_mul_f32 v[8:9], v[8:9], v[76:77]
	v_pk_mul_f32 v[4:5], v[4:5], v[80:81]
	v_pk_mul_f32 v[2:3], v[2:3], v[78:79]
	s_branch .Lmla_h0_cont
; __device__ __forceinline__ void qkt9(f32x16& p0, f32x16& p1, const char* Kn, const char* Kr, const v8i32* qf, const float init, int r32, int hi) {
;     ...
;   for (int r = 0; r < 16; ++r) { p0[r] = init; p1[r] = init; }
; __device__ __forceinline__ void partialSM9(f32x16& p0, f32x16& p1, float& m_run, float& alpha, const float thr2) {
;     ...
;   if (__builtin_expect(__all(pmax <= 7.0f + thr2), 1)) { alpha = 1.f; }
;   else { const float delta = fmaxf(pmax - 7.0f, 0.f); alpha = __builtin_amdgcn_exp2f(-delta); m_run += delta;
; #pragma unroll
;     for (int r = 0; r < 16; ++r) { p0[r] -= delta; p1[r] -= delta; } }
.Lmla_h1_newmax:
	v_add_f32_e32 v0, 0xc0a00000, v177
	v_max_f32_e32 v177, 0, v0
	v_exp_f32_e64 v218, -v177
	v_add_f32_e32 v217, v217, v177
	v_pk_add_f32 v[96:97], v[96:97], v[176:177] op_sel:[0,1] op_sel_hi:[1,1] neg_lo:[0,1] neg_hi:[0,1]
	v_pk_add_f32 v[94:95], v[94:95], v[176:177] op_sel:[0,1] op_sel_hi:[1,1] neg_lo:[0,1] neg_hi:[0,1]
	v_pk_add_f32 v[92:93], v[92:93], v[176:177] op_sel:[0,1] op_sel_hi:[1,1] neg_lo:[0,1] neg_hi:[0,1]
	v_pk_add_f32 v[90:91], v[90:91], v[176:177] op_sel:[0,1] op_sel_hi:[1,1] neg_lo:[0,1] neg_hi:[0,1]
	v_pk_add_f32 v[88:89], v[88:89], v[176:177] op_sel:[0,1] op_sel_hi:[1,1] neg_lo:[0,1] neg_hi:[0,1]
	v_pk_add_f32 v[86:87], v[86:87], v[176:177] op_sel:[0,1] op_sel_hi:[1,1] neg_lo:[0,1] neg_hi:[0,1]
	v_pk_add_f32 v[84:85], v[84:85], v[176:177] op_sel:[0,1] op_sel_hi:[1,1] neg_lo:[0,1] neg_hi:[0,1]
	v_pk_add_f32 v[82:83], v[82:83], v[176:177] op_sel:[0,1] op_sel_hi:[1,1] neg_lo:[0,1] neg_hi:[0,1]
	s_and_saveexec_b64 s[20:21], s[40:41]
	ds_write_b32 v208, v218 offset:41088
	s_or_b64 exec, exec, s[20:21]
	v_pk_add_f32 v[80:81], v[80:81], v[176:177] op_sel:[0,1] op_sel_hi:[1,1] neg_lo:[0,1] neg_hi:[0,1]
	v_pk_add_f32 v[78:79], v[78:79], v[176:177] op_sel:[0,1] op_sel_hi:[1,1] neg_lo:[0,1] neg_hi:[0,1]
	v_pk_add_f32 v[76:77], v[76:77], v[176:177] op_sel:[0,1] op_sel_hi:[1,1] neg_lo:[0,1] neg_hi:[0,1]
	v_pk_add_f32 v[74:75], v[74:75], v[176:177] op_sel:[0,1] op_sel_hi:[1,1] neg_lo:[0,1] neg_hi:[0,1]
	v_pk_add_f32 v[72:73], v[72:73], v[176:177] op_sel:[0,1] op_sel_hi:[1,1] neg_lo:[0,1] neg_hi:[0,1]
	v_pk_add_f32 v[70:71], v[70:71], v[176:177] op_sel:[0,1] op_sel_hi:[1,1] neg_lo:[0,1] neg_hi:[0,1]
	v_pk_add_f32 v[68:69], v[68:69], v[176:177] op_sel:[0,1] op_sel_hi:[1,1] neg_lo:[0,1] neg_hi:[0,1]
	v_pk_add_f32 v[66:67], v[66:67], v[176:177] op_sel:[0,1] op_sel_hi:[1,1] neg_lo:[0,1] neg_hi:[0,1]
	v_sub_f32_e32 v230, 0x40e00000, v217
	v_mov_b32_e32 v231, v230
	v_mov_b64_e32 v[232:233], v[230:231]
	v_mov_b64_e32 v[234:235], v[230:231]
	v_mov_b64_e32 v[236:237], v[230:231]
	v_mov_b64_e32 v[238:239], v[230:231]
	v_mov_b64_e32 v[240:241], v[230:231]
	v_mov_b64_e32 v[242:243], v[230:231]
	v_mov_b64_e32 v[244:245], v[230:231]
	v_add_u32_e32 v0, v187, v207
	s_waitcnt lgkmcnt(0)
	ds_read_b128 v[98:101], v0 offset:41184
	ds_read_b128 v[102:105], v0 offset:41152
	ds_read_b128 v[106:109], v0 offset:41120
	ds_read_b128 v[110:113], v0 offset:41088
	s_waitcnt lgkmcnt(0)
	v_pk_mul_f32 v[62:63], v[62:63], v[98:99]
	v_pk_mul_f32 v[58:59], v[58:59], v[102:103]
	v_pk_mul_f32 v[54:55], v[54:55], v[106:107]
	v_pk_mul_f32 v[64:65], v[64:65], v[100:101]
	v_pk_mul_f32 v[60:61], v[60:61], v[104:105]
	v_pk_mul_f32 v[56:57], v[56:57], v[108:109]
	v_pk_mul_f32 v[52:53], v[52:53], v[112:113]
	v_pk_mul_f32 v[50:51], v[50:51], v[110:111]
	v_pk_mul_f32 v[46:47], v[46:47], v[98:99]
	v_pk_mul_f32 v[42:43], v[42:43], v[102:103]
	v_pk_mul_f32 v[38:39], v[38:39], v[106:107]
	v_pk_mul_f32 v[48:49], v[48:49], v[100:101]
	v_pk_mul_f32 v[44:45], v[44:45], v[104:105]
	v_pk_mul_f32 v[40:41], v[40:41], v[108:109]
	v_pk_mul_f32 v[36:37], v[36:37], v[112:113]
	v_pk_mul_f32 v[34:35], v[34:35], v[110:111]
	v_pk_mul_f32 v[30:31], v[30:31], v[98:99]
	v_pk_mul_f32 v[26:27], v[26:27], v[102:103]
	v_pk_mul_f32 v[22:23], v[22:23], v[106:107]
	v_pk_mul_f32 v[32:33], v[32:33], v[100:101]
	v_pk_mul_f32 v[28:29], v[28:29], v[104:105]
	v_pk_mul_f32 v[24:25], v[24:25], v[108:109]
	v_pk_mul_f32 v[20:21], v[20:21], v[112:113]
	v_pk_mul_f32 v[18:19], v[18:19], v[110:111]
	v_pk_mul_f32 v[14:15], v[14:15], v[98:99]
	v_pk_mul_f32 v[10:11], v[10:11], v[102:103]
	v_pk_mul_f32 v[6:7], v[6:7], v[106:107]
	v_pk_mul_f32 v[16:17], v[16:17], v[100:101]
	v_pk_mul_f32 v[12:13], v[12:13], v[104:105]
	v_pk_mul_f32 v[8:9], v[8:9], v[108:109]
	v_pk_mul_f32 v[4:5], v[4:5], v[112:113]
	v_pk_mul_f32 v[2:3], v[2:3], v[110:111]
	s_branch .Lmla_h1_cont
